# chunk stage-5 output products: 27 LDS fragment reads software-pipelined 5 reads ahead into unused VGPRs, counted lgkmcnt (on top of gsync+cumsum version)
# speedup vs baseline: 1.0068x; 1.0001x over previous
; DI unsigned pk2(float a, float b) { f32x2 v = {a, b}; bfv2 r = __builtin_convertvector(v, bfv2); return __builtin_bit_cast(unsigned, r); }
; DI void chunk_item(const Params& p, int l, int item, char* lds) {
;     ...
;   {
;     const f32x4 z4 = (f32x4){0.f, 0.f, 0.f, 0.f};
;     bf16_t* gPT = p.cPT + (size_t)item * 4096;
;     const float wl_c = s_wl[wave * 16 + l15];
; #pragma unroll
;     for (int k1t = 0; k1t < 4; ++k1t) {
;       f32x4 d = mm16(s_XT + k1t * 16 * XLD, XLD, s_BmT + wave * 16 * XLD, XLD, 1, z4, l15, quad);
;       const int k2 = wave * 16 + l15, k1 = k1t * 16 + quad * 4;
;       float o[4];
; #pragma unroll
;       for (int e = 0; e < 4; ++e) o[e] = ((k1 + e == k2 ? 1.f : 0.f) - d[e]) * wl_c;
;       u32x2 ov; ov[0] = pk2(o[0], o[1]); ov[1] = pk2(o[2], o[3]);
;       *(u32x2*)(gPT + k2 * 64 + k1) = ov;
;     }
;     bf16_t* gG = p.cG + (size_t)item * 4096;
; #pragma unroll
;     for (int k2t = 0; k2t < 4; ++k2t) {
;       const f32x4 d1 = mm16(s_KpT + k2t * 16 * XLD, XLD, s_VmT + wave * 16 * XLD, XLD, 1, z4, l15, quad);
;       const f32x4 d2 = mm16(s_BmT + k2t * 16 * XLD, XLD, s_XT + (64 + wave * 16) * XLD, XLD, 1, z4, l15, quad);
;       const int k2 = k2t * 16 + quad * 4, v = wave * 16 + l15;
;       const f32x4 wv = *(const f32x4*)(s_wl + k2);
;       u32x2 ov; ov[0] = pk2((d1[0] - d2[0]) * wv[0], (d1[1] - d2[1]) * wv[1]); ov[1] = pk2((d1[2] - d2[2]) * wv[2], (d1[3] - d2[3]) * wv[3]);
;       *(u32x2*)(gG + v * 64 + k2) = ov;
.LBB0_257:
	s_or_b64 exec, exec, s[0:1]
	s_lshl_b64 s[26:27], s[24:25], 1
	s_add_u32 s0, s56, s26
	s_addc_u32 s1, s57, s27
	s_lshl_b32 s20, s44, 4
	v_or_b32_e32 v20, s20, v112
	v_lshlrev_b32_e32 v2, 6, v20
	v_lshlrev_b32_e32 v0, 2, v20
	s_mulk_i32 s44, 0x500
	v_ashrrev_i32_e32 v3, 31, v2
	s_waitcnt lgkmcnt(0)
	s_barrier
	ds_read_b32 v10, v0 offset:58880
	ds_read_b128 v[32:35], v115 offset:48640
	v_add3_u32 v12, s44, v125, v117
	ds_read_b128 v[36:39], v12 offset:20992
	ds_read_b128 v[40:43], v115 offset:49920
	ds_read_b128 v[44:47], v115 offset:51200
	ds_read_b128 v[48:51], v115 offset:52480
	v_lshlrev_b64 v[14:15], 1, v[2:3]
	ds_read_b128 v[52:55], v115 offset:26112
	ds_read_b128 v[56:59], v12 offset:31232
	s_waitcnt lgkmcnt(5)
	v_mfma_f32_16x16x32_bf16 v[2:5], v[32:35], v[36:39], 0
	v_lshl_add_u64 v[16:17], s[0:1], 0, v[14:15]
	v_cmp_eq_u32_e32 vcc, v85, v20
	v_cmp_eq_u32_e64 s[0:1], v118, v20
	v_or_b32_e32 v11, 48, v85
	v_cndmask_b32_e64 v18, 0, 1.0, vcc
	v_cndmask_b32_e64 v19, 0, 1.0, s[0:1]
	v_cmp_eq_u32_e32 vcc, v119, v20
	v_cmp_eq_u32_e64 s[0:1], v120, v20
	v_pk_add_f32 v[2:3], v[18:19], v[2:3] neg_lo:[0,1] neg_hi:[0,1]
	v_cndmask_b32_e64 v18, 0, 1.0, vcc
	v_cndmask_b32_e64 v19, 0, 1.0, s[0:1]
	v_pk_add_f32 v[4:5], v[18:19], v[4:5] neg_lo:[0,1] neg_hi:[0,1]
	v_pk_mul_f32 v[2:3], v[10:11], v[2:3] op_sel_hi:[0,1]
	v_pk_mul_f32 v[4:5], v[10:11], v[4:5] op_sel_hi:[0,1]
	v_lshlrev_b32_e32 v0, 1, v85
	v_cvt_pk_bf16_f32 v2, v2, v3
	v_cvt_pk_bf16_f32 v3, v4, v5
	v_lshl_add_u64 v[16:17], v[16:17], 0, v[0:1]
	global_store_dwordx2 v[16:17], v[2:3], off
	ds_read_b128 v[60:63], v115 offset:20992
	s_waitcnt lgkmcnt(5)
	v_mfma_f32_16x16x32_bf16 v[2:5], v[40:43], v[36:39], 0
	v_cmp_eq_u32_e32 vcc, v121, v20
	v_cmp_eq_u32_e64 s[0:1], v122, v20
	v_or_b32_e32 v13, 32, v85
	v_cndmask_b32_e64 v18, 0, 1.0, vcc
	v_cndmask_b32_e64 v19, 0, 1.0, s[0:1]
	v_cmp_eq_u32_e32 vcc, v123, v20
	v_cmp_eq_u32_e64 s[0:1], v124, v20
	s_nop 0
	v_pk_add_f32 v[2:3], v[18:19], v[2:3] neg_lo:[0,1] neg_hi:[0,1]
	v_cndmask_b32_e64 v18, 0, 1.0, vcc
	v_cndmask_b32_e64 v19, 0, 1.0, s[0:1]
	v_pk_add_f32 v[4:5], v[18:19], v[4:5] neg_lo:[0,1] neg_hi:[0,1]
	v_pk_mul_f32 v[2:3], v[10:11], v[2:3] op_sel_hi:[0,1]
	v_pk_mul_f32 v[4:5], v[10:11], v[4:5] op_sel_hi:[0,1]
	v_cvt_pk_bf16_f32 v2, v2, v3
	v_cvt_pk_bf16_f32 v3, v4, v5
	global_store_dwordx2 v[16:17], v[2:3], off offset:32
	ds_read_b128 v[64:67], v12 offset:53760
	s_waitcnt lgkmcnt(5)
	v_mfma_f32_16x16x32_bf16 v[2:5], v[44:47], v[36:39], 0
	v_or_b32_e32 v18, 33, v85
	v_cmp_eq_u32_e32 vcc, v13, v20
	v_cmp_eq_u32_e64 s[0:1], v18, v20
	v_or_b32_e32 v13, 35, v85
	v_cndmask_b32_e64 v18, 0, 1.0, vcc
	v_cndmask_b32_e64 v19, 0, 1.0, s[0:1]
	s_nop 1
	v_pk_add_f32 v[2:3], v[18:19], v[2:3] neg_lo:[0,1] neg_hi:[0,1]
	v_or_b32_e32 v18, 34, v85
	v_cmp_eq_u32_e32 vcc, v18, v20
	v_cmp_eq_u32_e64 s[0:1], v13, v20
	v_pk_mul_f32 v[2:3], v[10:11], v[2:3] op_sel_hi:[0,1]
	v_cndmask_b32_e64 v18, 0, 1.0, vcc
	v_cndmask_b32_e64 v19, 0, 1.0, s[0:1]
	v_pk_add_f32 v[4:5], v[18:19], v[4:5] neg_lo:[0,1] neg_hi:[0,1]
	v_cvt_pk_bf16_f32 v2, v2, v3
	v_pk_mul_f32 v[4:5], v[10:11], v[4:5] op_sel_hi:[0,1]
	v_cvt_pk_bf16_f32 v3, v4, v5
	global_store_dwordx2 v[16:17], v[2:3], off offset:64
	ds_read_b128 v[68:71], v89 offset:58880
	s_waitcnt lgkmcnt(5)
	v_mfma_f32_16x16x32_bf16 v[2:5], v[48:51], v[36:39], 0
	v_or_b32_e32 v6, 49, v85
	v_cmp_eq_u32_e32 vcc, v11, v20
	v_cmp_eq_u32_e64 s[0:1], v6, v20
	v_readlane_b32 s68, v254, 52
	v_cndmask_b32_e64 v6, 0, 1.0, vcc
	v_cndmask_b32_e64 v7, 0, 1.0, s[0:1]
	s_nop 1
	v_pk_add_f32 v[2:3], v[6:7], v[2:3] neg_lo:[0,1] neg_hi:[0,1]
	v_or_b32_e32 v6, 51, v85
	v_or_b32_e32 v7, 50, v85
	v_cmp_eq_u32_e32 vcc, v7, v20
	v_cmp_eq_u32_e64 s[0:1], v6, v20
	v_pk_mul_f32 v[2:3], v[10:11], v[2:3] op_sel_hi:[0,1]
	v_cndmask_b32_e64 v6, 0, 1.0, vcc
	v_cndmask_b32_e64 v7, 0, 1.0, s[0:1]
	v_pk_add_f32 v[4:5], v[6:7], v[4:5] neg_lo:[0,1] neg_hi:[0,1]
	v_cvt_pk_bf16_f32 v2, v2, v3
	v_pk_mul_f32 v[4:5], v[10:11], v[4:5] op_sel_hi:[0,1]
	v_cvt_pk_bf16_f32 v3, v4, v5
	global_store_dwordx2 v[16:17], v[2:3], off offset:96
	ds_read_b128 v[72:75], v115 offset:22272
	ds_read_b128 v[76:79], v115 offset:27392
	s_add_u32 s0, s58, s26
	s_addc_u32 s1, s59, s27
	v_lshl_add_u64 v[10:11], s[0:1], 0, v[14:15]
	s_waitcnt lgkmcnt(5)
	v_mfma_f32_16x16x32_bf16 v[14:17], v[52:55], v[56:59], 0
	ds_read_b128 v[214:217], v89 offset:58944
	ds_read_b128 v[222:225], v115 offset:23552
	ds_read_b128 v[226:229], v115 offset:28672
	v_lshl_add_u64 v[10:11], v[10:11], 0, v[0:1]
	s_waitcnt lgkmcnt(6)
	v_mfma_f32_16x16x32_bf16 v[18:21], v[60:63], v[64:67], 0
	s_add_u32 s0, s60, s24
	s_addc_u32 s1, s61, s25
	v_lshlrev_b32_e32 v0, 1, v113
	s_nop 4
	v_sub_f32_e32 v15, v15, v19
	v_sub_f32_e32 v14, v14, v18
	v_sub_f32_e32 v17, v17, v21
	v_sub_f32_e32 v16, v16, v20
	ds_read_b128 v[32:35], v89 offset:59008
	s_waitcnt lgkmcnt(6)
; DI unsigned pk2(float a, float b) { f32x2 v = {a, b}; bfv2 r = __builtin_convertvector(v, bfv2); return __builtin_bit_cast(unsigned, r); }
; DI float bf_lo(unsigned u) { return __uint_as_float(u << 16); }
; DI float bf_hi(unsigned u) { return __uint_as_float(u & 0xffff0000u); }
; DI void chunk_item(const Params& p, int l, int item, char* lds) {
;     ...
;     bf16_t* gG = p.cG + (size_t)item * 4096;
; #pragma unroll
;     for (int k2t = 0; k2t < 4; ++k2t) {
;       const f32x4 d1 = mm16(s_KpT + k2t * 16 * XLD, XLD, s_VmT + wave * 16 * XLD, XLD, 1, z4, l15, quad);
;       const f32x4 d2 = mm16(s_BmT + k2t * 16 * XLD, XLD, s_XT + (64 + wave * 16) * XLD, XLD, 1, z4, l15, quad);
;       const int k2 = k2t * 16 + quad * 4, v = wave * 16 + l15;
;       const f32x4 wv = *(const f32x4*)(s_wl + k2);
;       u32x2 ov; ov[0] = pk2((d1[0] - d2[0]) * wv[0], (d1[1] - d2[1]) * wv[1]); ov[1] = pk2((d1[2] - d2[2]) * wv[2], (d1[3] - d2[3]) * wv[3]);
;       *(u32x2*)(gG + v * 64 + k2) = ov;
;     }
;     bf16_t* gRT = p.cRT + (size_t)item * 2048;
;     bf16_t* gOI = p.cOI + (size_t)item * 2048;
; #pragma unroll
;     for (int ti = 0; ti < 2; ++ti) {
;       const f32x4 d = mm16(s_XT + wave * 16 * XLD, XLD, s_Mrb + ti * 16 * XLD, XLD, 1, z4, l15, quad);
;       const int t = ti * 16 + l15, k = wave * 16 + quad * 4;
;       const u32x2 rv = *(const u32x2*)(s_R + t * 72 + k);
;       u32x2 ov; ov[0] = pk2(bf_lo(rv[0]) - d[0], bf_hi(rv[0]) - d[1]); ov[1] = pk2(bf_lo(rv[1]) - d[2], bf_hi(rv[1]) - d[3]);
;       *(u32x2*)(gRT + t * 64 + k) = ov;
;       const f32x4 e1 = mm16(s_VmT + wave * 16 * XLD, XLD, s_Mrk + ti * 16 * XLD, XLD, 1, z4, l15, quad);
;       const f32x4 e2 = mm16(s_XT + (64 + wave * 16) * XLD, XLD, s_Mrb + ti * 16 * XLD, XLD, 1, z4, l15, quad);
;       u32x2 oo; oo[0] = pk2(e1[0] - e2[0], e1[1] - e2[1]); oo[1] = pk2(e1[2] - e2[2], e1[3] - e2[3]);
;       *(u32x2*)(gOI + t * 64 + k) = oo;
;     }
	v_pk_mul_f32 v[16:17], v[16:17], v[70:71]
	v_pk_mul_f32 v[14:15], v[14:15], v[68:69]
	s_waitcnt lgkmcnt(5)
	v_mfma_f32_16x16x32_bf16 v[18:21], v[72:75], v[64:67], 0
	v_cvt_pk_bf16_f32 v14, v14, v15
	v_cvt_pk_bf16_f32 v15, v16, v17
	global_store_dwordx2 v[10:11], v[14:15], off
	ds_read_b128 v[40:43], v115 offset:24832
	s_waitcnt lgkmcnt(5)
	v_mfma_f32_16x16x32_bf16 v[14:17], v[76:79], v[56:59], 0
	ds_read_b128 v[44:47], v115 offset:29952
	s_add_u32 s24, s62, s24
	s_addc_u32 s25, s63, s25
	s_nop 4
	v_sub_f32_e32 v15, v15, v19
	v_sub_f32_e32 v14, v14, v18
	v_sub_f32_e32 v17, v17, v21
	v_sub_f32_e32 v16, v16, v20
	ds_read_b128 v[36:39], v89 offset:59072
	s_waitcnt lgkmcnt(6)
	v_pk_mul_f32 v[16:17], v[16:17], v[216:217]
	v_pk_mul_f32 v[14:15], v[14:15], v[214:215]
	s_waitcnt lgkmcnt(5)
	v_mfma_f32_16x16x32_bf16 v[18:21], v[222:225], v[64:67], 0
	v_cvt_pk_bf16_f32 v14, v14, v15
	v_cvt_pk_bf16_f32 v15, v16, v17
	global_store_dwordx2 v[10:11], v[14:15], off offset:32
	ds_read_b128 v[48:51], v12 offset:48640
	s_waitcnt lgkmcnt(5)
	v_mfma_f32_16x16x32_bf16 v[14:17], v[226:229], v[56:59], 0
	ds_read_b128 v[52:55], v115 offset:41472
	v_readlane_b32 s74, v254, 58
	s_add_i32 s22, s22, s74
	s_nop 4
	v_sub_f32_e32 v15, v15, v19
	v_sub_f32_e32 v14, v14, v18
	v_sub_f32_e32 v17, v17, v21
	v_sub_f32_e32 v16, v16, v20
	s_waitcnt lgkmcnt(5)
	v_pk_mul_f32 v[16:17], v[16:17], v[34:35]
	v_pk_mul_f32 v[14:15], v[14:15], v[32:33]
	s_waitcnt lgkmcnt(4)
	v_mfma_f32_16x16x32_bf16 v[18:21], v[40:43], v[64:67], 0
	v_cvt_pk_bf16_f32 v14, v14, v15
	v_cvt_pk_bf16_f32 v15, v16, v17
	global_store_dwordx2 v[10:11], v[14:15], off offset:64
	s_waitcnt lgkmcnt(3)
	v_mfma_f32_16x16x32_bf16 v[14:17], v[44:47], v[56:59], 0
	s_cmpk_gt_i32 s22, 0xfff
	v_readlane_b32 s69, v254, 53
	v_readlane_b32 s70, v254, 54
	s_nop 4
	v_sub_f32_e32 v15, v15, v19
	v_sub_f32_e32 v14, v14, v18
	v_sub_f32_e32 v17, v17, v21
	v_sub_f32_e32 v16, v16, v20
	s_waitcnt lgkmcnt(2)
	v_pk_mul_f32 v[16:17], v[16:17], v[38:39]
	v_pk_mul_f32 v[14:15], v[14:15], v[36:37]
	v_readlane_b32 s71, v254, 55
	v_cvt_pk_bf16_f32 v14, v14, v15
	v_cvt_pk_bf16_f32 v15, v16, v17
	global_store_dwordx2 v[10:11], v[14:15], off offset:96
	v_or_b32_e32 v10, s20, v85
	v_ashrrev_i32_e32 v11, 31, v10
	v_lshl_add_u32 v30, v10, 1, v114
	ds_read_b64 v[80:81], v30 offset:16384
	ds_read_b128 v[60:63], v115 offset:38912
	ds_read_b128 v[68:71], v115 offset:42752
	ds_read_b64 v[72:73], v30 offset:18688
	ds_read_b128 v[76:79], v115 offset:40192
	v_lshlrev_b64 v[14:15], 1, v[10:11]
	s_waitcnt lgkmcnt(5)
	v_mfma_f32_16x16x32_bf16 v[26:29], v[48:51], v[52:55], 0
	v_lshl_add_u64 v[16:17], s[0:1], 0, v[14:15]
	v_lshl_add_u64 v[14:15], s[24:25], 0, v[14:15]
	v_readlane_b32 s72, v254, 56
	s_waitcnt lgkmcnt(4)
	v_lshlrev_b32_e32 v12, 16, v80
	v_and_b32_e32 v13, 0xffff0000, v80
	s_nop 1
	s_nop 0
	v_pk_add_f32 v[12:13], v[12:13], v[26:27] neg_lo:[0,1] neg_hi:[0,1]
	v_mfma_f32_16x16x32_bf16 v[22:25], v[64:67], v[52:55], 0
	v_cvt_pk_bf16_f32 v10, v12, v13
	v_lshlrev_b32_e32 v12, 16, v81
	v_and_b32_e32 v13, 0xffff0000, v81
	v_pk_add_f32 v[12:13], v[12:13], v[28:29] neg_lo:[0,1] neg_hi:[0,1]
	v_readlane_b32 s73, v254, 57
	v_cvt_pk_bf16_f32 v11, v12, v13
	v_lshl_add_u64 v[12:13], v[16:17], 0, v[0:1]
	global_store_dwordx2 v[12:13], v[10:11], off
	s_waitcnt lgkmcnt(3)
	v_mfma_f32_16x16x32_bf16 v[10:13], v[56:59], v[60:63], 0
	v_readlane_b32 s75, v254, 59
	s_nop 6
	v_sub_f32_e32 v13, v13, v25
	v_sub_f32_e32 v12, v12, v24
	v_sub_f32_e32 v11, v11, v23
	v_sub_f32_e32 v10, v10, v22
	v_cvt_pk_bf16_f32 v10, v10, v11
	v_cvt_pk_bf16_f32 v11, v12, v13
	v_lshl_add_u64 v[12:13], v[14:15], 0, v[0:1]
	global_store_dwordx2 v[12:13], v[10:11], off
	s_waitcnt lgkmcnt(2)
	v_mfma_f32_16x16x32_bf16 v[18:21], v[48:51], v[68:71], 0
	s_waitcnt lgkmcnt(1)
	v_lshlrev_b32_e32 v24, 16, v72
	v_and_b32_e32 v25, 0xffff0000, v72
	v_lshlrev_b32_e32 v22, 16, v73
	v_and_b32_e32 v23, 0xffff0000, v73
	s_nop 2
	s_nop 0
	v_pk_add_f32 v[18:19], v[24:25], v[18:19] neg_lo:[0,1] neg_hi:[0,1]
	v_pk_add_f32 v[20:21], v[22:23], v[20:21] neg_lo:[0,1] neg_hi:[0,1]
	v_lshlrev_b32_e32 v0, 7, v116
	v_cvt_pk_bf16_f32 v18, v18, v19
	v_cvt_pk_bf16_f32 v19, v20, v21
	v_lshl_add_u64 v[16:17], v[16:17], 0, v[0:1]
	global_store_dwordx2 v[16:17], v[18:19], off
	s_waitcnt lgkmcnt(0)
	v_mfma_f32_16x16x32_bf16 v[2:5], v[56:59], v[76:79], 0
	v_mfma_f32_16x16x32_bf16 v[6:9], v[64:67], v[68:71], 0
	s_nop 7
	v_sub_f32_e32 v5, v5, v9
	v_sub_f32_e32 v4, v4, v8
	v_sub_f32_e32 v3, v3, v7
	v_sub_f32_e32 v2, v2, v6
	v_cvt_pk_bf16_f32 v2, v2, v3
	v_cvt_pk_bf16_f32 v3, v4, v5
	v_lshl_add_u64 v[4:5], v[14:15], 0, v[0:1]
	global_store_dwordx2 v[4:5], v[2:3], off
	s_barrier
	s_cbranch_scc1 .LBB0_371
